# prologue weight conversion: nt (streaming) hint on the 56 bf16 weight-copy stores
# baseline (speedup 1.0000x reference)
; #define GAS __attribute__((address_space(1)))
; #define LAS __attribute__((address_space(3)))
; DI unsigned pk2(float lo, float hi) { const f32x2 v = {lo, hi}; const bf16x2_t b = __builtin_convertvector(v, bf16x2_t); return __builtin_bit_cast(unsigned, b); }
; #define LDS_WAIT() asm volatile("s_waitcnt lgkmcnt(0)" ::: "memory")
; DI void conv_item(const float* W, int K, int Nsrc, bf16* Wt, const float* kscale, int mapid, LAS bf16* tile, int item, int nblk, int lane) {
;     ...
; #pragma unroll
;     for (int q = 0; q < 8; ++q) { u32x4 o; o.x = pk2(v[8 * q], v[8 * q + 1]); o.y = pk2(v[8 * q + 2], v[8 * q + 3]); o.z = pk2(v[8 * q + 4], v[8 * q + 5]); o.w = pk2(v[8 * q + 6], v[8 * q + 7]);
;         *(LAS u32x4*)(tile + lane * 72 + 8 * q) = o; }
;     LDS_WAIT(); asm volatile("" ::: "memory");
; #pragma unroll
;     for (int i = 0; i < 8; ++i) { const int r = i * 8 + (lane >> 3), c8 = lane & 7;
;         *(GAS u32x4*)(Wt + (size_t)(n0 + r) * K + k0 + 8 * c8) = *(const LAS u32x4*)(tile + r * 72 + 8 * c8); }
;     LDS_WAIT(); asm volatile("" ::: "memory");
; DI void conv_job(Frame& F, const ConvJob j, int& base) {
;     ...
;     for (int it = first; it < nitems; it += NGW) conv_item(j.W, j.K, j.Nsrc, j.Wt, j.kscale, j.mapid, tile, it, nblk, F.lane);
.LBB0_347:
	s_waitcnt vmcnt(0)
	v_cvt_pk_bf16_f32 v98, v26, v27
	v_cvt_pk_bf16_f32 v99, v24, v25
	v_add_u32_e32 v4, s29, v1
	v_cvt_pk_bf16_f32 v24, v38, v39
	v_cvt_pk_bf16_f32 v25, v36, v37
	v_cvt_pk_bf16_f32 v26, v34, v35
	v_cvt_pk_bf16_f32 v27, v32, v33
	ds_write_b128 v4, v[24:27] offset:16
	v_cvt_pk_bf16_f32 v24, v46, v47
	v_cvt_pk_bf16_f32 v25, v44, v45
	v_cvt_pk_bf16_f32 v26, v42, v43
	v_cvt_pk_bf16_f32 v27, v40, v41
	ds_write_b128 v4, v[24:27] offset:32
	v_cvt_pk_bf16_f32 v24, v54, v55
	v_cvt_pk_bf16_f32 v25, v52, v53
	v_cvt_pk_bf16_f32 v26, v50, v51
	v_cvt_pk_bf16_f32 v27, v48, v49
	ds_write_b128 v4, v[24:27] offset:48
	v_cvt_pk_bf16_f32 v24, v62, v63
	v_cvt_pk_bf16_f32 v25, v60, v61
	v_cvt_pk_bf16_f32 v26, v58, v59
	v_cvt_pk_bf16_f32 v27, v56, v57
	ds_write_b128 v4, v[24:27] offset:64
	v_cvt_pk_bf16_f32 v24, v70, v71
	v_cvt_pk_bf16_f32 v25, v68, v69
	v_cvt_pk_bf16_f32 v26, v66, v67
	v_cvt_pk_bf16_f32 v27, v64, v65
	ds_write_b128 v4, v[24:27] offset:80
	v_cvt_pk_bf16_f32 v24, v78, v79
	v_cvt_pk_bf16_f32 v25, v76, v77
	v_cvt_pk_bf16_f32 v26, v74, v75
	v_cvt_pk_bf16_f32 v27, v72, v73
	v_cvt_pk_bf16_f32 v96, v30, v31
	v_cvt_pk_bf16_f32 v97, v28, v29
	ds_write_b128 v4, v[24:27] offset:96
	v_cvt_pk_bf16_f32 v24, v86, v87
	v_cvt_pk_bf16_f32 v25, v84, v85
	v_cvt_pk_bf16_f32 v26, v82, v83
	v_cvt_pk_bf16_f32 v27, v80, v81
	ds_write_b128 v4, v[96:99]
	ds_write_b128 v4, v[24:27] offset:112
	s_waitcnt lgkmcnt(0)
	v_add_u32_e32 v4, v90, v91
	ds_read_b128 v[24:27], v4
	v_add_u32_e32 v34, s10, v89
	v_ashrrev_i32_e32 v35, 31, v34
	v_lshl_add_u64 v[32:33], s[26:27], 1, v[22:23]
	v_lshlrev_b64 v[28:29], 12, v[34:35]
	v_lshl_add_u64 v[36:37], v[32:33], 0, v[28:29]
	ds_read_b128 v[28:31], v4 offset:1152
	s_waitcnt lgkmcnt(0)
	global_store_dwordx4 v[36:37], v[24:27], off nt
	v_readlane_b32 s10, v254, 18
	s_add_i32 s0, s0, s38
	v_add_u32_e32 v24, 8, v34
	v_ashrrev_i32_e32 v25, 31, v24
	v_lshlrev_b64 v[24:25], 12, v[24:25]
	v_lshl_add_u64 v[24:25], v[32:33], 0, v[24:25]
	global_store_dwordx4 v[24:25], v[28:31], off nt
	ds_read_b128 v[24:27], v4 offset:2304
	s_add_i32 s9, s9, s10
	v_add_u32_e32 v28, 16, v34
	v_ashrrev_i32_e32 v29, 31, v28
	v_lshlrev_b64 v[28:29], 12, v[28:29]
	v_lshl_add_u64 v[36:37], v[32:33], 0, v[28:29]
	ds_read_b128 v[28:31], v4 offset:3456
	s_waitcnt lgkmcnt(1)
	global_store_dwordx4 v[36:37], v[24:27], off nt
	s_add_i32 s15, s15, s30
	s_cmpk_lt_i32 s0, 0x1600
	v_add_u32_e32 v24, 24, v34
	v_ashrrev_i32_e32 v25, 31, v24
	v_lshlrev_b64 v[24:25], 12, v[24:25]
	v_lshl_add_u64 v[24:25], v[32:33], 0, v[24:25]
	s_waitcnt lgkmcnt(0)
	global_store_dwordx4 v[24:25], v[28:31], off nt
	ds_read_b128 v[24:27], v4 offset:4608
	s_nop 0
	v_add_u32_e32 v28, 32, v34
	v_ashrrev_i32_e32 v29, 31, v28
	v_lshlrev_b64 v[28:29], 12, v[28:29]
	v_lshl_add_u64 v[36:37], v[32:33], 0, v[28:29]
	ds_read_b128 v[28:31], v4 offset:5760
	s_waitcnt lgkmcnt(1)
	global_store_dwordx4 v[36:37], v[24:27], off nt
	s_nop 1
	v_add_u32_e32 v24, 40, v34
	v_ashrrev_i32_e32 v25, 31, v24
	v_lshlrev_b64 v[24:25], 12, v[24:25]
	v_lshl_add_u64 v[24:25], v[32:33], 0, v[24:25]
	s_waitcnt lgkmcnt(0)
	global_store_dwordx4 v[24:25], v[28:31], off nt
	ds_read_b128 v[24:27], v4 offset:6912
	s_nop 0
	v_add_u32_e32 v28, 48, v34
	v_ashrrev_i32_e32 v29, 31, v28
	v_lshlrev_b64 v[28:29], 12, v[28:29]
	v_lshl_add_u64 v[36:37], v[32:33], 0, v[28:29]
	ds_read_b128 v[28:31], v4 offset:8064
	s_waitcnt lgkmcnt(1)
	global_store_dwordx4 v[36:37], v[24:27], off nt
	s_nop 1
	v_add_u32_e32 v24, 56, v34
	v_ashrrev_i32_e32 v25, 31, v24
	v_lshlrev_b64 v[24:25], 12, v[24:25]
	v_lshl_add_u64 v[24:25], v[32:33], 0, v[24:25]
	s_waitcnt lgkmcnt(0)
	global_store_dwordx4 v[24:25], v[28:31], off nt
	s_waitcnt lgkmcnt(0)
	s_cbranch_scc0 .LBB0_352

; #define GAS __attribute__((address_space(1)))
; #define LAS __attribute__((address_space(3)))
; DI unsigned pk2(float lo, float hi) { const f32x2 v = {lo, hi}; const bf16x2_t b = __builtin_convertvector(v, bf16x2_t); return __builtin_bit_cast(unsigned, b); }
; #define LDS_WAIT() asm volatile("s_waitcnt lgkmcnt(0)" ::: "memory")
; DI void conv_item(const float* W, int K, int Nsrc, bf16* Wt, const float* kscale, int mapid, LAS bf16* tile, int item, int nblk, int lane) {
;     ...
; #pragma unroll
;     for (int q = 0; q < 8; ++q) { u32x4 o; o.x = pk2(v[8 * q], v[8 * q + 1]); o.y = pk2(v[8 * q + 2], v[8 * q + 3]); o.z = pk2(v[8 * q + 4], v[8 * q + 5]); o.w = pk2(v[8 * q + 6], v[8 * q + 7]);
;         *(LAS u32x4*)(tile + lane * 72 + 8 * q) = o; }
;     LDS_WAIT(); asm volatile("" ::: "memory");
; #pragma unroll
;     for (int i = 0; i < 8; ++i) { const int r = i * 8 + (lane >> 3), c8 = lane & 7;
;         *(GAS u32x4*)(Wt + (size_t)(n0 + r) * K + k0 + 8 * c8) = *(const LAS u32x4*)(tile + r * 72 + 8 * c8); }
;     LDS_WAIT(); asm volatile("" ::: "memory");
; DI void conv_job(Frame& F, const ConvJob j, int& base) {
;     ...
;     for (int it = first; it < nitems; it += NGW) conv_item(j.W, j.K, j.Nsrc, j.Wt, j.kscale, j.mapid, tile, it, nblk, F.lane);
.LBB0_354:
	s_or_b64 exec, exec, s[26:27]
	s_waitcnt vmcnt(0)
	v_cvt_pk_bf16_f32 v97, v32, v31
	v_cvt_pk_bf16_f32 v98, v29, v28
	v_cvt_pk_bf16_f32 v99, v4, v30
	v_add_u32_e32 v4, s29, v1
	v_cvt_pk_bf16_f32 v28, v42, v41
	v_cvt_pk_bf16_f32 v29, v40, v39
	v_cvt_pk_bf16_f32 v30, v37, v36
	v_cvt_pk_bf16_f32 v31, v35, v38
	ds_write_b128 v4, v[28:31] offset:16
	v_cvt_pk_bf16_f32 v28, v50, v49
	v_cvt_pk_bf16_f32 v29, v48, v47
	v_cvt_pk_bf16_f32 v30, v45, v44
	v_cvt_pk_bf16_f32 v31, v43, v46
	ds_write_b128 v4, v[28:31] offset:32
	v_cvt_pk_bf16_f32 v28, v58, v57
	v_cvt_pk_bf16_f32 v29, v56, v55
	v_cvt_pk_bf16_f32 v30, v53, v52
	v_cvt_pk_bf16_f32 v31, v51, v54
	ds_write_b128 v4, v[28:31] offset:48
	v_cvt_pk_bf16_f32 v28, v66, v65
	v_cvt_pk_bf16_f32 v29, v64, v63
	v_cvt_pk_bf16_f32 v30, v61, v60
	v_cvt_pk_bf16_f32 v31, v59, v62
	ds_write_b128 v4, v[28:31] offset:64
	v_cvt_pk_bf16_f32 v28, v74, v73
	v_cvt_pk_bf16_f32 v29, v72, v71
	v_cvt_pk_bf16_f32 v30, v69, v68
	v_cvt_pk_bf16_f32 v31, v67, v70
	ds_write_b128 v4, v[28:31] offset:80
	v_cvt_pk_bf16_f32 v28, v82, v81
	v_cvt_pk_bf16_f32 v29, v80, v79
	v_cvt_pk_bf16_f32 v30, v77, v76
	v_cvt_pk_bf16_f32 v31, v75, v78
	v_cvt_pk_bf16_f32 v96, v34, v33
	ds_write_b128 v4, v[28:31] offset:96
	v_cvt_pk_bf16_f32 v28, v95, v87
	v_cvt_pk_bf16_f32 v29, v86, v85
	v_cvt_pk_bf16_f32 v30, v84, v83
	v_cvt_pk_bf16_f32 v31, v24, v25
	ds_write_b128 v4, v[96:99]
	ds_write_b128 v4, v[28:31] offset:112
	s_waitcnt lgkmcnt(0)
	v_add_u32_e32 v4, v90, v91
	ds_read_b128 v[28:31], v4
	ds_read_b128 v[32:35], v4 offset:1152
	s_sub_i32 s8, 0, s8
	s_add_i32 s8, s8, s7
	v_lshl_add_u64 v[24:25], s[16:17], 1, v[22:23]
	v_add_u32_e32 v38, s8, v26
	s_movk_i32 s10, 0x2c00
	v_mad_i64_i32 v[36:37], s[8:9], v38, s10, v[24:25]
	s_waitcnt lgkmcnt(0)
	global_store_dwordx4 v[36:37], v[28:31], off nt
	s_add_i32 s0, s0, s38
	v_add_u32_e32 v26, s30, v26
	v_add_u32_e32 v28, 8, v38
	v_mad_i64_i32 v[28:29], s[8:9], v28, s10, v[24:25]
	global_store_dwordx4 v[28:29], v[32:35], off nt
	ds_read_b128 v[28:31], v4 offset:2304
	s_cmpk_lt_i32 s0, 0xb00
	v_add_u32_e32 v32, 16, v38
	v_mad_i64_i32 v[36:37], s[8:9], v32, s10, v[24:25]
	ds_read_b128 v[32:35], v4 offset:3456
	s_waitcnt lgkmcnt(1)
	global_store_dwordx4 v[36:37], v[28:31], off nt
	v_add_u32_e32 v27, s30, v27
	s_nop 0
	v_add_u32_e32 v28, 24, v38
	v_mad_i64_i32 v[28:29], s[8:9], v28, s10, v[24:25]
	s_waitcnt lgkmcnt(0)
	global_store_dwordx4 v[28:29], v[32:35], off nt
	ds_read_b128 v[28:31], v4 offset:4608
	s_nop 0
	v_add_u32_e32 v32, 32, v38
	v_mad_i64_i32 v[36:37], s[8:9], v32, s10, v[24:25]
	ds_read_b128 v[32:35], v4 offset:5760
	s_waitcnt lgkmcnt(1)
	global_store_dwordx4 v[36:37], v[28:31], off nt
	s_nop 1
	v_add_u32_e32 v28, 40, v38
	v_mad_i64_i32 v[28:29], s[8:9], v28, s10, v[24:25]
	s_waitcnt lgkmcnt(0)
	global_store_dwordx4 v[28:29], v[32:35], off nt
	ds_read_b128 v[28:31], v4 offset:6912
	s_nop 0
	v_add_u32_e32 v32, 48, v38
	v_mad_i64_i32 v[36:37], s[8:9], v32, s10, v[24:25]
	ds_read_b128 v[32:35], v4 offset:8064
	v_add_u32_e32 v4, 56, v38
	v_mad_i64_i32 v[24:25], s[8:9], v4, s10, v[24:25]
	s_waitcnt lgkmcnt(1)
	global_store_dwordx4 v[36:37], v[28:31], off nt
	s_waitcnt lgkmcnt(0)
	global_store_dwordx4 v[24:25], v[32:35], off nt
	s_waitcnt lgkmcnt(0)
	s_cbranch_scc0 .LBB0_357

; #define GAS __attribute__((address_space(1)))
; #define LAS __attribute__((address_space(3)))
; DI unsigned pk2(float lo, float hi) { const f32x2 v = {lo, hi}; const bf16x2_t b = __builtin_convertvector(v, bf16x2_t); return __builtin_bit_cast(unsigned, b); }
; #define LDS_WAIT() asm volatile("s_waitcnt lgkmcnt(0)" ::: "memory")
; DI void conv_item(const float* W, int K, int Nsrc, bf16* Wt, const float* kscale, int mapid, LAS bf16* tile, int item, int nblk, int lane) {
;     ...
; #pragma unroll
;     for (int q = 0; q < 8; ++q) { u32x4 o; o.x = pk2(v[8 * q], v[8 * q + 1]); o.y = pk2(v[8 * q + 2], v[8 * q + 3]); o.z = pk2(v[8 * q + 4], v[8 * q + 5]); o.w = pk2(v[8 * q + 6], v[8 * q + 7]);
;         *(LAS u32x4*)(tile + lane * 72 + 8 * q) = o; }
;     LDS_WAIT(); asm volatile("" ::: "memory");
; #pragma unroll
;     for (int i = 0; i < 8; ++i) { const int r = i * 8 + (lane >> 3), c8 = lane & 7;
;         *(GAS u32x4*)(Wt + (size_t)(n0 + r) * K + k0 + 8 * c8) = *(const LAS u32x4*)(tile + r * 72 + 8 * c8); }
;     LDS_WAIT(); asm volatile("" ::: "memory");
; DI void conv_job(Frame& F, const ConvJob j, int& base) {
;     ...
;     for (int it = first; it < nitems; it += NGW) conv_item(j.W, j.K, j.Nsrc, j.Wt, j.kscale, j.mapid, tile, it, nblk, F.lane);
.LBB0_359:
	s_or_b64 exec, exec, s[26:27]
	s_waitcnt vmcnt(0)
	v_cvt_pk_bf16_f32 v97, v32, v31
	v_cvt_pk_bf16_f32 v98, v29, v28
	v_cvt_pk_bf16_f32 v99, v4, v30
	v_add_u32_e32 v4, s29, v1
	v_cvt_pk_bf16_f32 v28, v42, v41
	v_cvt_pk_bf16_f32 v29, v40, v39
	v_cvt_pk_bf16_f32 v30, v37, v36
	v_cvt_pk_bf16_f32 v31, v35, v38
	ds_write_b128 v4, v[28:31] offset:16
	v_cvt_pk_bf16_f32 v28, v50, v49
	v_cvt_pk_bf16_f32 v29, v48, v47
	v_cvt_pk_bf16_f32 v30, v45, v44
	v_cvt_pk_bf16_f32 v31, v43, v46
	ds_write_b128 v4, v[28:31] offset:32
	v_cvt_pk_bf16_f32 v28, v58, v57
	v_cvt_pk_bf16_f32 v29, v56, v55
	v_cvt_pk_bf16_f32 v30, v53, v52
	v_cvt_pk_bf16_f32 v31, v51, v54
	ds_write_b128 v4, v[28:31] offset:48
	v_cvt_pk_bf16_f32 v28, v66, v65
	v_cvt_pk_bf16_f32 v29, v64, v63
	v_cvt_pk_bf16_f32 v30, v61, v60
	v_cvt_pk_bf16_f32 v31, v59, v62
	ds_write_b128 v4, v[28:31] offset:64
	v_cvt_pk_bf16_f32 v28, v74, v73
	v_cvt_pk_bf16_f32 v29, v72, v71
	v_cvt_pk_bf16_f32 v30, v69, v68
	v_cvt_pk_bf16_f32 v31, v67, v70
	ds_write_b128 v4, v[28:31] offset:80
	v_cvt_pk_bf16_f32 v28, v82, v81
	v_cvt_pk_bf16_f32 v29, v80, v79
	v_cvt_pk_bf16_f32 v30, v77, v76
	v_cvt_pk_bf16_f32 v31, v75, v78
	v_cvt_pk_bf16_f32 v96, v34, v33
	ds_write_b128 v4, v[28:31] offset:96
	v_cvt_pk_bf16_f32 v28, v95, v87
	v_cvt_pk_bf16_f32 v29, v86, v85
	v_cvt_pk_bf16_f32 v30, v84, v83
	v_cvt_pk_bf16_f32 v31, v24, v25
	ds_write_b128 v4, v[96:99]
	ds_write_b128 v4, v[28:31] offset:112
	s_waitcnt lgkmcnt(0)
	s_sub_i32 s8, 0, s8
	v_add_u32_e32 v4, v90, v91
	ds_read_b128 v[28:31], v4
	s_add_i32 s8, s8, s7
	v_add_u32_e32 v36, s8, v26
	v_ashrrev_i32_e32 v37, 31, v36
	v_lshl_add_u64 v[24:25], s[16:17], 1, v[22:23]
	v_lshlrev_b64 v[32:33], 12, v[36:37]
	v_lshl_add_u64 v[38:39], v[24:25], 0, v[32:33]
	ds_read_b128 v[32:35], v4 offset:1152
	s_waitcnt lgkmcnt(0)
	global_store_dwordx4 v[38:39], v[28:31], off nt
	s_add_i32 s0, s0, s38
	v_add_u32_e32 v26, s30, v26
	v_add_u32_e32 v28, 8, v36
	v_ashrrev_i32_e32 v29, 31, v28
	v_lshlrev_b64 v[28:29], 12, v[28:29]
	v_lshl_add_u64 v[28:29], v[24:25], 0, v[28:29]
	global_store_dwordx4 v[28:29], v[32:35], off nt
	ds_read_b128 v[28:31], v4 offset:2304
	s_cmpk_lt_i32 s0, 0x400
	v_add_u32_e32 v32, 16, v36
	v_ashrrev_i32_e32 v33, 31, v32
	v_lshlrev_b64 v[32:33], 12, v[32:33]
	v_lshl_add_u64 v[38:39], v[24:25], 0, v[32:33]
	ds_read_b128 v[32:35], v4 offset:3456
	s_waitcnt lgkmcnt(1)
	global_store_dwordx4 v[38:39], v[28:31], off nt
	v_add_u32_e32 v27, s30, v27
	s_nop 0
	v_add_u32_e32 v28, 24, v36
	v_ashrrev_i32_e32 v29, 31, v28
	v_lshlrev_b64 v[28:29], 12, v[28:29]
	v_lshl_add_u64 v[28:29], v[24:25], 0, v[28:29]
	s_waitcnt lgkmcnt(0)
	global_store_dwordx4 v[28:29], v[32:35], off nt
	ds_read_b128 v[28:31], v4 offset:4608
	s_nop 0
	v_add_u32_e32 v32, 32, v36
	v_ashrrev_i32_e32 v33, 31, v32
	v_lshlrev_b64 v[32:33], 12, v[32:33]
	v_lshl_add_u64 v[38:39], v[24:25], 0, v[32:33]
	ds_read_b128 v[32:35], v4 offset:5760
	s_waitcnt lgkmcnt(1)
	global_store_dwordx4 v[38:39], v[28:31], off nt
	s_nop 1
	v_add_u32_e32 v28, 40, v36
	v_ashrrev_i32_e32 v29, 31, v28
	v_lshlrev_b64 v[28:29], 12, v[28:29]
	v_lshl_add_u64 v[28:29], v[24:25], 0, v[28:29]
	s_waitcnt lgkmcnt(0)
	global_store_dwordx4 v[28:29], v[32:35], off nt
	ds_read_b128 v[28:31], v4 offset:6912
	s_nop 0
	v_add_u32_e32 v32, 48, v36
	v_ashrrev_i32_e32 v33, 31, v32
	v_lshlrev_b64 v[32:33], 12, v[32:33]
	v_lshl_add_u64 v[38:39], v[24:25], 0, v[32:33]
	ds_read_b128 v[32:35], v4 offset:8064
	s_waitcnt lgkmcnt(1)
	global_store_dwordx4 v[38:39], v[28:31], off nt
	s_nop 1
	v_add_u32_e32 v28, 56, v36
	v_ashrrev_i32_e32 v29, 31, v28
	v_lshlrev_b64 v[28:29], 12, v[28:29]
	v_lshl_add_u64 v[24:25], v[24:25], 0, v[28:29]
	s_waitcnt lgkmcnt(0)
	global_store_dwordx4 v[24:25], v[32:35], off nt
	s_waitcnt lgkmcnt(0)
	s_cbranch_scc0 .LBB0_362

; #define GAS __attribute__((address_space(1)))
; #define LAS __attribute__((address_space(3)))
; DI unsigned pk2(float lo, float hi) { const f32x2 v = {lo, hi}; const bf16x2_t b = __builtin_convertvector(v, bf16x2_t); return __builtin_bit_cast(unsigned, b); }
; #define LDS_WAIT() asm volatile("s_waitcnt lgkmcnt(0)" ::: "memory")
; DI void conv_item(const float* W, int K, int Nsrc, bf16* Wt, const float* kscale, int mapid, LAS bf16* tile, int item, int nblk, int lane) {
;     ...
;     for (int q = 0; q < 8; ++q) { u32x4 o; o.x = pk2(v[8 * q], v[8 * q + 1]); o.y = pk2(v[8 * q + 2], v[8 * q + 3]); o.z = pk2(v[8 * q + 4], v[8 * q + 5]); o.w = pk2(v[8 * q + 6], v[8 * q + 7]);
;         *(LAS u32x4*)(tile + lane * 72 + 8 * q) = o; }
;     LDS_WAIT(); asm volatile("" ::: "memory");
; #pragma unroll
;     for (int i = 0; i < 8; ++i) { const int r = i * 8 + (lane >> 3), c8 = lane & 7;
;         *(GAS u32x4*)(Wt + (size_t)(n0 + r) * K + k0 + 8 * c8) = *(const LAS u32x4*)(tile + r * 72 + 8 * c8); }
;     LDS_WAIT(); asm volatile("" ::: "memory");
; DI void p_prologue(Frame& F, const Args& a) {
;     ...
;             conv_job(F, ConvJob{a.in[31] + ((size_t)l * 4 + n) * 512 * D, (bf16*)(ws + WS_WBR) + ((size_t)l * 4 + n) * D * 512, nullptr, 512, D, D, 0}, base);
.LBB0_366:
	s_or_b64 exec, exec, s[34:35]
	s_waitcnt vmcnt(0)
	v_cvt_pk_bf16_f32 v97, v32, v31
	v_cvt_pk_bf16_f32 v98, v29, v28
	v_cvt_pk_bf16_f32 v99, v4, v30
	v_add_u32_e32 v4, s29, v1
	v_cvt_pk_bf16_f32 v28, v42, v41
	v_cvt_pk_bf16_f32 v29, v40, v39
	v_cvt_pk_bf16_f32 v30, v37, v36
	v_cvt_pk_bf16_f32 v31, v35, v38
	ds_write_b128 v4, v[28:31] offset:16
	v_cvt_pk_bf16_f32 v28, v50, v49
	v_cvt_pk_bf16_f32 v29, v48, v47
	v_cvt_pk_bf16_f32 v30, v45, v44
	v_cvt_pk_bf16_f32 v31, v43, v46
	ds_write_b128 v4, v[28:31] offset:32
	v_cvt_pk_bf16_f32 v28, v58, v57
	v_cvt_pk_bf16_f32 v29, v56, v55
	v_cvt_pk_bf16_f32 v30, v53, v52
	v_cvt_pk_bf16_f32 v31, v51, v54
	ds_write_b128 v4, v[28:31] offset:48
	v_cvt_pk_bf16_f32 v28, v66, v65
	v_cvt_pk_bf16_f32 v29, v64, v63
	v_cvt_pk_bf16_f32 v30, v61, v60
	v_cvt_pk_bf16_f32 v31, v59, v62
	ds_write_b128 v4, v[28:31] offset:64
	v_cvt_pk_bf16_f32 v28, v74, v73
	v_cvt_pk_bf16_f32 v29, v72, v71
	v_cvt_pk_bf16_f32 v30, v69, v68
	v_cvt_pk_bf16_f32 v31, v67, v70
	ds_write_b128 v4, v[28:31] offset:80
	v_cvt_pk_bf16_f32 v28, v82, v81
	v_cvt_pk_bf16_f32 v29, v80, v79
	v_cvt_pk_bf16_f32 v30, v77, v76
	v_cvt_pk_bf16_f32 v31, v75, v78
	v_cvt_pk_bf16_f32 v96, v34, v33
	ds_write_b128 v4, v[28:31] offset:96
	v_cvt_pk_bf16_f32 v28, v95, v87
	v_cvt_pk_bf16_f32 v29, v86, v85
	v_cvt_pk_bf16_f32 v30, v84, v83
	v_cvt_pk_bf16_f32 v31, v24, v25
	ds_write_b128 v4, v[96:99]
	ds_write_b128 v4, v[28:31] offset:112
	s_waitcnt lgkmcnt(0)
	s_sub_i32 s10, 0, s10
	v_add_u32_e32 v4, v90, v91
	ds_read_b128 v[28:31], v4
	s_add_i32 s10, s10, s9
	v_add_u32_e32 v36, s10, v26
	v_ashrrev_i32_e32 v37, 31, v36
	v_lshl_add_u64 v[24:25], s[26:27], 1, v[22:23]
	v_lshlrev_b64 v[32:33], 10, v[36:37]
	v_lshl_add_u64 v[38:39], v[24:25], 0, v[32:33]
	ds_read_b128 v[32:35], v4 offset:1152
	s_waitcnt lgkmcnt(0)
	global_store_dwordx4 v[38:39], v[28:31], off nt
	s_add_i32 s6, s6, s38
	v_add_u32_e32 v26, s30, v26
	v_add_u32_e32 v28, 8, v36
	v_ashrrev_i32_e32 v29, 31, v28
	v_lshlrev_b64 v[28:29], 10, v[28:29]
	v_lshl_add_u64 v[28:29], v[24:25], 0, v[28:29]
	global_store_dwordx4 v[28:29], v[32:35], off nt
	ds_read_b128 v[28:31], v4 offset:2304
	s_cmpk_lt_i32 s6, 0x100
	v_add_u32_e32 v32, 16, v36
	v_ashrrev_i32_e32 v33, 31, v32
	v_lshlrev_b64 v[32:33], 10, v[32:33]
	v_lshl_add_u64 v[38:39], v[24:25], 0, v[32:33]
	ds_read_b128 v[32:35], v4 offset:3456
	s_waitcnt lgkmcnt(1)
	global_store_dwordx4 v[38:39], v[28:31], off nt
	v_add_u32_e32 v27, s30, v27
	s_nop 0
	v_add_u32_e32 v28, 24, v36
	v_ashrrev_i32_e32 v29, 31, v28
	v_lshlrev_b64 v[28:29], 10, v[28:29]
	v_lshl_add_u64 v[28:29], v[24:25], 0, v[28:29]
	s_waitcnt lgkmcnt(0)
	global_store_dwordx4 v[28:29], v[32:35], off nt
	ds_read_b128 v[28:31], v4 offset:4608
	s_nop 0
	v_add_u32_e32 v32, 32, v36
	v_ashrrev_i32_e32 v33, 31, v32
	v_lshlrev_b64 v[32:33], 10, v[32:33]
	v_lshl_add_u64 v[38:39], v[24:25], 0, v[32:33]
	ds_read_b128 v[32:35], v4 offset:5760
	s_waitcnt lgkmcnt(1)
	global_store_dwordx4 v[38:39], v[28:31], off nt
	s_nop 1
	v_add_u32_e32 v28, 40, v36
	v_ashrrev_i32_e32 v29, 31, v28
	v_lshlrev_b64 v[28:29], 10, v[28:29]
	v_lshl_add_u64 v[28:29], v[24:25], 0, v[28:29]
	s_waitcnt lgkmcnt(0)
	global_store_dwordx4 v[28:29], v[32:35], off nt
	ds_read_b128 v[28:31], v4 offset:6912
	s_nop 0
	v_add_u32_e32 v32, 48, v36
	v_ashrrev_i32_e32 v33, 31, v32
	v_lshlrev_b64 v[32:33], 10, v[32:33]
	v_lshl_add_u64 v[38:39], v[24:25], 0, v[32:33]
	ds_read_b128 v[32:35], v4 offset:8064
	s_waitcnt lgkmcnt(1)
	global_store_dwordx4 v[38:39], v[28:31], off nt
	s_nop 1
	v_add_u32_e32 v28, 56, v36
	v_ashrrev_i32_e32 v29, 31, v28
	v_lshlrev_b64 v[28:29], 10, v[28:29]
	v_lshl_add_u64 v[24:25], v[24:25], 0, v[28:29]
	s_waitcnt lgkmcnt(0)
	global_store_dwordx4 v[24:25], v[32:35], off nt
	s_waitcnt lgkmcnt(0)
	s_cbranch_scc0 .LBB0_369

; #define GAS __attribute__((address_space(1)))
; #define LAS __attribute__((address_space(3)))
; DI unsigned pk2(float lo, float hi) { const f32x2 v = {lo, hi}; const bf16x2_t b = __builtin_convertvector(v, bf16x2_t); return __builtin_bit_cast(unsigned, b); }
; #define LDS_WAIT() asm volatile("s_waitcnt lgkmcnt(0)" ::: "memory")
; DI void conv_item(const float* W, int K, int Nsrc, bf16* Wt, const float* kscale, int mapid, LAS bf16* tile, int item, int nblk, int lane) {
;     ...
;     for (int q = 0; q < 8; ++q) { u32x4 o; o.x = pk2(v[8 * q], v[8 * q + 1]); o.y = pk2(v[8 * q + 2], v[8 * q + 3]); o.z = pk2(v[8 * q + 4], v[8 * q + 5]); o.w = pk2(v[8 * q + 6], v[8 * q + 7]);
;         *(LAS u32x4*)(tile + lane * 72 + 8 * q) = o; }
;     LDS_WAIT(); asm volatile("" ::: "memory");
; #pragma unroll
;     for (int i = 0; i < 8; ++i) { const int r = i * 8 + (lane >> 3), c8 = lane & 7;
;         *(GAS u32x4*)(Wt + (size_t)(n0 + r) * K + k0 + 8 * c8) = *(const LAS u32x4*)(tile + r * 72 + 8 * c8); }
;     LDS_WAIT(); asm volatile("" ::: "memory");
; DI void p_prologue(Frame& F, const Args& a) {
;     ...
;         conv_job(F, ConvJob{a.in[12] + (size_t)l * 512 * 768, (bf16*)(ws + WS_WQB) + (size_t)l * 1024 * 512, a.in[11] + (size_t)l * 512, 512, 768, 1024, 3}, base);
.LBB0_374:
	s_waitcnt vmcnt(0)
	v_cvt_pk_bf16_f32 v98, v26, v27
	v_cvt_pk_bf16_f32 v99, v24, v25
	v_add_u32_e32 v4, s29, v1
	v_cvt_pk_bf16_f32 v24, v38, v39
	v_cvt_pk_bf16_f32 v25, v36, v37
	v_cvt_pk_bf16_f32 v26, v34, v35
	v_cvt_pk_bf16_f32 v27, v32, v33
	ds_write_b128 v4, v[24:27] offset:16
	v_cvt_pk_bf16_f32 v24, v46, v47
	v_cvt_pk_bf16_f32 v25, v44, v45
	v_cvt_pk_bf16_f32 v26, v42, v43
	v_cvt_pk_bf16_f32 v27, v40, v41
	ds_write_b128 v4, v[24:27] offset:32
	v_cvt_pk_bf16_f32 v24, v54, v55
	v_cvt_pk_bf16_f32 v25, v52, v53
	v_cvt_pk_bf16_f32 v26, v50, v51
	v_cvt_pk_bf16_f32 v27, v48, v49
	ds_write_b128 v4, v[24:27] offset:48
	v_cvt_pk_bf16_f32 v24, v62, v63
	v_cvt_pk_bf16_f32 v25, v60, v61
	v_cvt_pk_bf16_f32 v26, v58, v59
	v_cvt_pk_bf16_f32 v27, v56, v57
	ds_write_b128 v4, v[24:27] offset:64
	v_cvt_pk_bf16_f32 v24, v70, v71
	v_cvt_pk_bf16_f32 v25, v68, v69
	v_cvt_pk_bf16_f32 v26, v66, v67
	v_cvt_pk_bf16_f32 v27, v64, v65
	ds_write_b128 v4, v[24:27] offset:80
	v_cvt_pk_bf16_f32 v24, v78, v79
	v_cvt_pk_bf16_f32 v25, v76, v77
	v_cvt_pk_bf16_f32 v26, v74, v75
	v_cvt_pk_bf16_f32 v27, v72, v73
	v_cvt_pk_bf16_f32 v96, v30, v31
	v_cvt_pk_bf16_f32 v97, v28, v29
	ds_write_b128 v4, v[24:27] offset:96
	v_cvt_pk_bf16_f32 v24, v86, v87
	v_cvt_pk_bf16_f32 v25, v84, v85
	v_cvt_pk_bf16_f32 v26, v82, v83
	v_cvt_pk_bf16_f32 v27, v80, v81
	ds_write_b128 v4, v[96:99]
	ds_write_b128 v4, v[24:27] offset:112
	s_waitcnt lgkmcnt(0)
	s_sub_i32 s10, 0, s10
	v_add_u32_e32 v4, v90, v91
	ds_read_b128 v[24:27], v4
	s_add_i32 s10, s10, s34
	v_add_u32_e32 v34, s10, v89
	v_ashrrev_i32_e32 v35, 31, v34
	v_lshl_add_u64 v[32:33], s[14:15], 1, v[22:23]
	v_lshlrev_b64 v[28:29], 10, v[34:35]
	v_lshl_add_u64 v[36:37], v[32:33], 0, v[28:29]
	ds_read_b128 v[28:31], v4 offset:1152
	s_waitcnt lgkmcnt(0)
	global_store_dwordx4 v[36:37], v[24:27], off nt
	s_add_i32 s1, s1, s38
	s_add_i32 s34, s34, s30
	v_add_u32_e32 v24, 8, v34
	v_ashrrev_i32_e32 v25, 31, v24
	v_lshlrev_b64 v[24:25], 10, v[24:25]
	v_lshl_add_u64 v[24:25], v[32:33], 0, v[24:25]
	global_store_dwordx4 v[24:25], v[28:31], off nt
	ds_read_b128 v[24:27], v4 offset:2304
	s_cmpk_lt_i32 s1, 0x80
	v_add_u32_e32 v28, 16, v34
	v_ashrrev_i32_e32 v29, 31, v28
	v_lshlrev_b64 v[28:29], 10, v[28:29]
	v_lshl_add_u64 v[36:37], v[32:33], 0, v[28:29]
	ds_read_b128 v[28:31], v4 offset:3456
	s_waitcnt lgkmcnt(1)
	global_store_dwordx4 v[36:37], v[24:27], off nt
	s_nop 1
	v_add_u32_e32 v24, 24, v34
	v_ashrrev_i32_e32 v25, 31, v24
	v_lshlrev_b64 v[24:25], 10, v[24:25]
	v_lshl_add_u64 v[24:25], v[32:33], 0, v[24:25]
	s_waitcnt lgkmcnt(0)
	global_store_dwordx4 v[24:25], v[28:31], off nt
	ds_read_b128 v[24:27], v4 offset:4608
	s_nop 0
	v_add_u32_e32 v28, 32, v34
	v_ashrrev_i32_e32 v29, 31, v28
	v_lshlrev_b64 v[28:29], 10, v[28:29]
	v_lshl_add_u64 v[36:37], v[32:33], 0, v[28:29]
	ds_read_b128 v[28:31], v4 offset:5760
	s_waitcnt lgkmcnt(1)
	global_store_dwordx4 v[36:37], v[24:27], off nt
	s_nop 1
	v_add_u32_e32 v24, 40, v34
	v_ashrrev_i32_e32 v25, 31, v24
	v_lshlrev_b64 v[24:25], 10, v[24:25]
	v_lshl_add_u64 v[24:25], v[32:33], 0, v[24:25]
	s_waitcnt lgkmcnt(0)
	global_store_dwordx4 v[24:25], v[28:31], off nt
	ds_read_b128 v[24:27], v4 offset:6912
	s_nop 0
	v_add_u32_e32 v28, 48, v34
	v_ashrrev_i32_e32 v29, 31, v28
	v_lshlrev_b64 v[28:29], 10, v[28:29]
	v_lshl_add_u64 v[36:37], v[32:33], 0, v[28:29]
	ds_read_b128 v[28:31], v4 offset:8064
	s_waitcnt lgkmcnt(1)
	global_store_dwordx4 v[36:37], v[24:27], off nt
	s_nop 1
	v_add_u32_e32 v24, 56, v34
	v_ashrrev_i32_e32 v25, 31, v24
	v_lshlrev_b64 v[24:25], 10, v[24:25]
	v_lshl_add_u64 v[24:25], v[32:33], 0, v[24:25]
	s_waitcnt lgkmcnt(0)
	global_store_dwordx4 v[24:25], v[28:31], off nt
	s_waitcnt lgkmcnt(0)
	s_cbranch_scc0 .LBB0_391

; #define GAS __attribute__((address_space(1)))
; #define LAS __attribute__((address_space(3)))
; DI unsigned pk2(float lo, float hi) { const f32x2 v = {lo, hi}; const bf16x2_t b = __builtin_convertvector(v, bf16x2_t); return __builtin_bit_cast(unsigned, b); }
; #define LDS_WAIT() asm volatile("s_waitcnt lgkmcnt(0)" ::: "memory")
; DI void conv_item(const float* W, int K, int Nsrc, bf16* Wt, const float* kscale, int mapid, LAS bf16* tile, int item, int nblk, int lane) {
;     ...
;     for (int q = 0; q < 8; ++q) { u32x4 o; o.x = pk2(v[8 * q], v[8 * q + 1]); o.y = pk2(v[8 * q + 2], v[8 * q + 3]); o.z = pk2(v[8 * q + 4], v[8 * q + 5]); o.w = pk2(v[8 * q + 6], v[8 * q + 7]);
;         *(LAS u32x4*)(tile + lane * 72 + 8 * q) = o; }
;     LDS_WAIT(); asm volatile("" ::: "memory");
; #pragma unroll
;     for (int i = 0; i < 8; ++i) { const int r = i * 8 + (lane >> 3), c8 = lane & 7;
;         *(GAS u32x4*)(Wt + (size_t)(n0 + r) * K + k0 + 8 * c8) = *(const LAS u32x4*)(tile + r * 72 + 8 * c8); }
;     LDS_WAIT(); asm volatile("" ::: "memory");
; DI void p_prologue(Frame& F, const Args& a) {
;     ...
;         conv_job(F, ConvJob{a.in[14] + (size_t)l * 256 * 1024, (bf16*)(ws + WS_WKVB) + (size_t)l * 1024 * 256, a.in[13] + (size_t)l * 256, 256, 1024, 1024, 0}, base);
.LBB0_394:
	s_waitcnt vmcnt(0)
	v_cvt_pk_bf16_f32 v99, v84, v85
	v_cvt_pk_bf16_f32 v100, v82, v83
	v_add_u32_e32 v4, s29, v1
	v_cvt_pk_bf16_f32 v83, v26, v27
	v_cvt_pk_bf16_f32 v84, v24, v25
	v_cvt_pk_bf16_f32 v24, v38, v39
	v_cvt_pk_bf16_f32 v25, v36, v37
	v_cvt_pk_bf16_f32 v26, v34, v35
	v_cvt_pk_bf16_f32 v27, v40, v41
	ds_write_b128 v4, v[24:27] offset:32
	v_cvt_pk_bf16_f32 v24, v46, v47
	v_cvt_pk_bf16_f32 v25, v44, v45
	v_cvt_pk_bf16_f32 v26, v42, v43
	v_cvt_pk_bf16_f32 v27, v48, v49
	ds_write_b128 v4, v[24:27] offset:48
	v_cvt_pk_bf16_f32 v24, v54, v55
	v_cvt_pk_bf16_f32 v25, v52, v53
	v_cvt_pk_bf16_f32 v26, v50, v51
	v_cvt_pk_bf16_f32 v27, v56, v57
	ds_write_b128 v4, v[24:27] offset:64
	v_cvt_pk_bf16_f32 v24, v62, v63
	v_cvt_pk_bf16_f32 v25, v60, v61
	v_cvt_pk_bf16_f32 v26, v58, v59
	v_cvt_pk_bf16_f32 v27, v64, v65
	ds_write_b128 v4, v[24:27] offset:80
	v_cvt_pk_bf16_f32 v24, v70, v71
	v_cvt_pk_bf16_f32 v25, v68, v69
	v_cvt_pk_bf16_f32 v26, v66, v67
	v_cvt_pk_bf16_f32 v27, v72, v73
	v_cvt_pk_bf16_f32 v98, v86, v87
	v_cvt_pk_bf16_f32 v101, v32, v33
	v_cvt_pk_bf16_f32 v82, v28, v29
	v_cvt_pk_bf16_f32 v85, v30, v31
	ds_write_b128 v4, v[24:27] offset:96
	v_cvt_pk_bf16_f32 v24, v78, v79
	v_cvt_pk_bf16_f32 v25, v76, v77
	v_cvt_pk_bf16_f32 v26, v74, v75
	v_cvt_pk_bf16_f32 v27, v80, v81
	ds_write_b128 v4, v[98:101]
	ds_write_b128 v4, v[82:85] offset:16
	ds_write_b128 v4, v[24:27] offset:112
	s_waitcnt lgkmcnt(0)
	s_sub_i32 s11, 0, s11
	v_add_u32_e32 v4, v90, v91
	ds_read_b128 v[24:27], v4
	s_add_i32 s11, s11, s10
	v_add_u32_e32 v34, s11, v95
	v_ashrrev_i32_e32 v35, 31, v34
	v_lshl_add_u64 v[32:33], s[14:15], 1, v[22:23]
	v_lshlrev_b64 v[28:29], 9, v[34:35]
	v_lshl_add_u64 v[36:37], v[32:33], 0, v[28:29]
	ds_read_b128 v[28:31], v4 offset:1152
	s_waitcnt lgkmcnt(0)
	global_store_dwordx4 v[36:37], v[24:27], off nt
	s_add_i32 s1, s1, s38
	v_add_u32_e32 v95, s30, v95
	v_add_u32_e32 v24, 8, v34
	v_ashrrev_i32_e32 v25, 31, v24
	v_lshlrev_b64 v[24:25], 9, v[24:25]
	v_lshl_add_u64 v[24:25], v[32:33], 0, v[24:25]
	global_store_dwordx4 v[24:25], v[28:31], off nt
	ds_read_b128 v[24:27], v4 offset:2304
	s_cmp_lt_i32 s1, 64
	v_add_u32_e32 v28, 16, v34
	v_ashrrev_i32_e32 v29, 31, v28
	v_lshlrev_b64 v[28:29], 9, v[28:29]
	v_lshl_add_u64 v[36:37], v[32:33], 0, v[28:29]
	ds_read_b128 v[28:31], v4 offset:3456
	s_waitcnt lgkmcnt(1)
	global_store_dwordx4 v[36:37], v[24:27], off nt
	v_add_u32_e32 v96, s30, v96
	s_nop 0
	v_add_u32_e32 v24, 24, v34
	v_ashrrev_i32_e32 v25, 31, v24
	v_lshlrev_b64 v[24:25], 9, v[24:25]
	v_lshl_add_u64 v[24:25], v[32:33], 0, v[24:25]
	s_waitcnt lgkmcnt(0)
	global_store_dwordx4 v[24:25], v[28:31], off nt
	ds_read_b128 v[24:27], v4 offset:4608
	s_nop 0
	v_add_u32_e32 v28, 32, v34
	v_ashrrev_i32_e32 v29, 31, v28
	v_lshlrev_b64 v[28:29], 9, v[28:29]
	v_lshl_add_u64 v[36:37], v[32:33], 0, v[28:29]
	ds_read_b128 v[28:31], v4 offset:5760
	s_waitcnt lgkmcnt(1)
	global_store_dwordx4 v[36:37], v[24:27], off nt
	s_nop 1
	v_add_u32_e32 v24, 40, v34
	v_ashrrev_i32_e32 v25, 31, v24
	v_lshlrev_b64 v[24:25], 9, v[24:25]
	v_lshl_add_u64 v[24:25], v[32:33], 0, v[24:25]
	s_waitcnt lgkmcnt(0)
	global_store_dwordx4 v[24:25], v[28:31], off nt
	ds_read_b128 v[24:27], v4 offset:6912
	s_nop 0
	v_add_u32_e32 v28, 48, v34
	v_ashrrev_i32_e32 v29, 31, v28
	v_lshlrev_b64 v[28:29], 9, v[28:29]
	v_lshl_add_u64 v[36:37], v[32:33], 0, v[28:29]
	ds_read_b128 v[28:31], v4 offset:8064
	s_waitcnt lgkmcnt(1)
	global_store_dwordx4 v[36:37], v[24:27], off nt
	s_nop 1
	v_add_u32_e32 v24, 56, v34
	v_ashrrev_i32_e32 v25, 31, v24
	v_lshlrev_b64 v[24:25], 9, v[24:25]
	v_lshl_add_u64 v[24:25], v[32:33], 0, v[24:25]
	s_waitcnt lgkmcnt(0)
	global_store_dwordx4 v[24:25], v[28:31], off nt
	s_waitcnt lgkmcnt(0)
	s_cbranch_scc0 .LBB0_399

; #define GAS __attribute__((address_space(1)))
; #define LAS __attribute__((address_space(3)))
; DI unsigned pk2(float lo, float hi) { const f32x2 v = {lo, hi}; const bf16x2_t b = __builtin_convertvector(v, bf16x2_t); return __builtin_bit_cast(unsigned, b); }
; #define LDS_WAIT() asm volatile("s_waitcnt lgkmcnt(0)" ::: "memory")
; DI void conv_item(const float* W, int K, int Nsrc, bf16* Wt, const float* kscale, int mapid, LAS bf16* tile, int item, int nblk, int lane) {
;     ...
;     for (int q = 0; q < 8; ++q) { u32x4 o; o.x = pk2(v[8 * q], v[8 * q + 1]); o.y = pk2(v[8 * q + 2], v[8 * q + 3]); o.z = pk2(v[8 * q + 4], v[8 * q + 5]); o.w = pk2(v[8 * q + 6], v[8 * q + 7]);
;         *(LAS u32x4*)(tile + lane * 72 + 8 * q) = o; }
;     LDS_WAIT(); asm volatile("" ::: "memory");
; #pragma unroll
;     for (int i = 0; i < 8; ++i) { const int r = i * 8 + (lane >> 3), c8 = lane & 7;
;         *(GAS u32x4*)(Wt + (size_t)(n0 + r) * K + k0 + 8 * c8) = *(const LAS u32x4*)(tile + r * 72 + 8 * c8); }
;     LDS_WAIT(); asm volatile("" ::: "memory");
; DI void p_prologue(Frame& F, const Args& a) {
;     ...
;         if (l > 0) conv_job(F, ConvJob{a.in[24] + (size_t)(l - 1) * 512 * 32, (bf16*)(ws + WS_WV1) + (size_t)l * 256 * 512, nullptr, 512, 32, 256, 4}, base);
.LBB0_402:
	s_or_b64 exec, exec, s[16:17]
	s_waitcnt vmcnt(0)
	v_cvt_pk_bf16_f32 v96, v95, v87
	v_cvt_pk_bf16_f32 v97, v86, v85
	v_cvt_pk_bf16_f32 v98, v84, v83
	v_cvt_pk_bf16_f32 v99, v82, v81
	v_add_u32_e32 v84, s29, v1
	v_cvt_pk_bf16_f32 v80, v80, v79
	v_cvt_pk_bf16_f32 v81, v78, v77
	v_cvt_pk_bf16_f32 v82, v76, v75
	v_cvt_pk_bf16_f32 v83, v74, v73
	v_cvt_pk_bf16_f32 v72, v72, v71
	v_cvt_pk_bf16_f32 v73, v70, v69
	v_cvt_pk_bf16_f32 v74, v68, v67
	v_cvt_pk_bf16_f32 v75, v66, v65
	v_cvt_pk_bf16_f32 v64, v64, v63
	v_cvt_pk_bf16_f32 v65, v62, v61
	v_cvt_pk_bf16_f32 v66, v60, v59
	v_cvt_pk_bf16_f32 v67, v58, v57
	v_cvt_pk_bf16_f32 v56, v56, v55
	v_cvt_pk_bf16_f32 v57, v54, v53
	v_cvt_pk_bf16_f32 v58, v52, v51
	v_cvt_pk_bf16_f32 v59, v50, v49
	v_cvt_pk_bf16_f32 v48, v48, v47
	v_cvt_pk_bf16_f32 v49, v46, v45
	v_cvt_pk_bf16_f32 v50, v44, v43
	v_cvt_pk_bf16_f32 v51, v42, v41
	v_cvt_pk_bf16_f32 v40, v40, v39
	v_cvt_pk_bf16_f32 v41, v38, v37
	v_cvt_pk_bf16_f32 v42, v36, v35
	v_cvt_pk_bf16_f32 v43, v34, v33
	v_cvt_pk_bf16_f32 v32, v32, v31
	v_cvt_pk_bf16_f32 v33, v30, v29
	v_cvt_pk_bf16_f32 v34, v28, v27
	v_cvt_pk_bf16_f32 v35, v26, v4
	ds_write_b128 v84, v[96:99]
	ds_write_b128 v84, v[80:83] offset:16
	ds_write_b128 v84, v[72:75] offset:32
	ds_write_b128 v84, v[64:67] offset:48
	ds_write_b128 v84, v[56:59] offset:64
	ds_write_b128 v84, v[48:51] offset:80
	ds_write_b128 v84, v[40:43] offset:96
	ds_write_b128 v84, v[32:35] offset:112
	s_waitcnt lgkmcnt(0)
	s_sub_i32 s9, 0, s9
	v_add_u32_e32 v4, v90, v91
	ds_read_b128 v[26:29], v4
	s_add_i32 s9, s9, s8
	v_add_u32_e32 v36, s9, v24
	v_ashrrev_i32_e32 v37, 31, v36
	v_lshl_add_u64 v[34:35], s[14:15], 1, v[22:23]
	v_lshlrev_b64 v[30:31], 10, v[36:37]
	v_lshl_add_u64 v[38:39], v[34:35], 0, v[30:31]
	ds_read_b128 v[30:33], v4 offset:1152
	s_waitcnt lgkmcnt(0)
	global_store_dwordx4 v[38:39], v[26:29], off nt
	s_add_i32 s1, s1, s38
	v_add_u32_e32 v24, s30, v24
	v_add_u32_e32 v26, 8, v36
	v_ashrrev_i32_e32 v27, 31, v26
	v_lshlrev_b64 v[26:27], 10, v[26:27]
	v_lshl_add_u64 v[26:27], v[34:35], 0, v[26:27]
	global_store_dwordx4 v[26:27], v[30:33], off nt
	ds_read_b128 v[26:29], v4 offset:2304
	s_cmp_lt_i32 s1, 32
	v_add_u32_e32 v30, 16, v36
	v_ashrrev_i32_e32 v31, 31, v30
	v_lshlrev_b64 v[30:31], 10, v[30:31]
	v_lshl_add_u64 v[38:39], v[34:35], 0, v[30:31]
	ds_read_b128 v[30:33], v4 offset:3456
	s_waitcnt lgkmcnt(1)
	global_store_dwordx4 v[38:39], v[26:29], off nt
	v_add_u32_e32 v25, s30, v25
	s_nop 0
	v_add_u32_e32 v26, 24, v36
	v_ashrrev_i32_e32 v27, 31, v26
	v_lshlrev_b64 v[26:27], 10, v[26:27]
	v_lshl_add_u64 v[26:27], v[34:35], 0, v[26:27]
	s_waitcnt lgkmcnt(0)
	global_store_dwordx4 v[26:27], v[30:33], off nt
	ds_read_b128 v[26:29], v4 offset:4608
	s_nop 0
	v_add_u32_e32 v30, 32, v36
	v_ashrrev_i32_e32 v31, 31, v30
	v_lshlrev_b64 v[30:31], 10, v[30:31]
	v_lshl_add_u64 v[38:39], v[34:35], 0, v[30:31]
	ds_read_b128 v[30:33], v4 offset:5760
	s_waitcnt lgkmcnt(1)
	global_store_dwordx4 v[38:39], v[26:29], off nt
	s_nop 1
	v_add_u32_e32 v26, 40, v36
	v_ashrrev_i32_e32 v27, 31, v26
	v_lshlrev_b64 v[26:27], 10, v[26:27]
	v_lshl_add_u64 v[26:27], v[34:35], 0, v[26:27]
	s_waitcnt lgkmcnt(0)
	global_store_dwordx4 v[26:27], v[30:33], off nt
	ds_read_b128 v[26:29], v4 offset:6912
	s_nop 0
	v_add_u32_e32 v30, 48, v36
	v_ashrrev_i32_e32 v31, 31, v30
	v_lshlrev_b64 v[30:31], 10, v[30:31]
	v_lshl_add_u64 v[38:39], v[34:35], 0, v[30:31]
	ds_read_b128 v[30:33], v4 offset:8064
	s_waitcnt lgkmcnt(1)
	global_store_dwordx4 v[38:39], v[26:29], off nt
	s_nop 1
	v_add_u32_e32 v26, 56, v36
	v_ashrrev_i32_e32 v27, 31, v26
	v_lshlrev_b64 v[26:27], 10, v[26:27]
	v_lshl_add_u64 v[26:27], v[34:35], 0, v[26:27]
	s_waitcnt lgkmcnt(0)
	global_store_dwordx4 v[26:27], v[30:33], off nt
	s_waitcnt lgkmcnt(0)
	s_cbranch_scc0 .LBB0_309
